# v18 + SWA output epilogue: loads of gated-merge chunks 1-5 issued with chunk 0's, chunks 6-7 once two register pairs are free; exact in-order waits (were 7 serialized round trips)
# speedup vs baseline: 1.0009x; 1.0009x over previous
; __device__ __forceinline__ unsigned pk2(float lo, float hi) { f32x2_t v = {lo, hi}; bf16x2_t b = __builtin_convertvector(v, bf16x2_t); return __builtin_bit_cast(unsigned, b); }
; __device__ __forceinline__ float bflo(unsigned u) { return __uint_as_float(u << 16); }
; __device__ __forceinline__ float bfhi(unsigned u) { return __uint_as_float(u & 0xffff0000u); }
;     ...
;     float lt = lrun;
;     if (MODE == 1) lt += __builtin_amdgcn_exp2f(sink2 - mrun);
;     const float inv = 1.f / lt;
; #pragma unroll
;     for (int db = 0; db < NDB; ++db)
; #pragma unroll
;         for (int r = 0; r < 16; ++r) o[db][r] *= inv;
; template <int DV, bool ACCUM>
; __device__ __forceinline__ void attn_store(const f32x16 (&o)[DV / 32], const bf16_t* gate_row, bf16_t* merged_row, int h) {
; #pragma unroll
;     for (int db = 0; db < DV / 32; ++db)
; #pragma unroll
;         for (int rg = 0; rg < 4; ++rg) {
;             const int d = 32 * db + 8 * rg + 4 * h;
;             const u32x2 g = *(const u32x2*)(gate_row + d);
;             float v0 = o[db][4 * rg + 0] * bflo(g.x), v1 = o[db][4 * rg + 1] * bfhi(g.x), v2 = o[db][4 * rg + 2] * bflo(g.y), v3 = o[db][4 * rg + 3] * bfhi(g.y);
;             if (ACCUM) { const u32x2 mm = *(const u32x2*)(merged_row + d); v0 += bflo(mm.x); v1 += bfhi(mm.x); v2 += bflo(mm.y); v3 += bfhi(mm.y); }
;             u32x2 w; w.x = pk2(v0, v1); w.y = pk2(v2, v3);
;             *(u32x2*)(merged_row + d) = w;
;             if (rg == 3) __builtin_amdgcn_sched_barrier(0);
;         }
.LBB0_820:
	v_fma_f32 v0, v122, s53, -v127
	v_exp_f32_e32 v0, v0
	s_lshl_b32 s4, s44, 6
	s_lshl_b32 s40, s4, 1
	s_movk_i32 s4, 0x3000
	v_add_f32_e32 v0, v34, v0
	v_div_scale_f32 v34, s[6:7], v0, v0, 1.0
	v_rcp_f32_e32 v35, v34
	s_nop 0
	v_fma_f32 v36, -v34, v35, 1.0
	v_fmac_f32_e32 v35, v36, v35
	v_div_scale_f32 v36, vcc, 1.0, v0, 1.0
	v_mul_f32_e32 v37, v36, v35
	v_fma_f32 v38, -v34, v37, v36
	v_fmac_f32_e32 v37, v38, v35
	v_fma_f32 v34, -v34, v37, v36
	v_div_fmas_f32 v34, v34, v35, v37
	v_div_fixup_f32 v36, v34, v0, 1.0
	v_mbcnt_lo_u32_b32 v0, -1, 0
	v_mbcnt_hi_u32_b32 v0, -1, v0
	v_mov_b64_e32 v[34:35], s[96:97]
	v_and_or_b32 v37, v0, 31, s29
	v_mad_u64_u32 v[34:35], s[6:7], v37, s52, v[34:35]
	v_add_u32_e32 v35, s35, v35
	v_lshrrev_b32_e32 v0, 2, v0
	v_lshl_add_u64 v[34:35], v[34:35], 0, s[40:41]
	v_and_b32_e32 v0, 8, v0
	v_lshl_add_u64 v[40:41], v[34:35], 0, v[0:1]
	v_add_co_u32_e32 v34, vcc, s4, v40
	s_mov_b64 s[6:7], 0x3200
	s_nop 0
	v_addc_co_u32_e32 v35, vcc, 0, v41, vcc
	s_movk_i32 s4, 0x2000
	v_lshl_add_u64 v[38:39], v[40:41], 0, s[6:7]
	global_load_dwordx2 v[42:43], v[34:35], off offset:512
	v_lshl_add_u64 v[34:35], v[40:41], 0, s[46:47]
	v_add_co_u32_e32 v40, vcc, s4, v40
	v_pk_mul_f32 v[2:3], v[2:3], v[36:37] op_sel_hi:[1,0]
	s_nop 0
	v_addc_co_u32_e32 v41, vcc, 0, v41, vcc
	global_load_dwordx2 v[44:45], v[40:41], off offset:2560
	global_load_dwordx2 v[226:227], v[38:39], off offset:16
	global_load_dwordx2 v[228:229], v[34:35], off offset:16
	global_load_dwordx2 v[230:231], v[38:39], off offset:32
	global_load_dwordx2 v[232:233], v[34:35], off offset:32
	global_load_dwordx2 v[234:235], v[38:39], off offset:48
	global_load_dwordx2 v[236:237], v[34:35], off offset:48
	global_load_dwordx2 v[242:243], v[38:39], off offset:64
	global_load_dwordx2 v[244:245], v[34:35], off offset:64
	global_load_dwordx2 v[246:247], v[38:39], off offset:80
	global_load_dwordx2 v[248:249], v[34:35], off offset:80
	v_pk_mul_f32 v[4:5], v[4:5], v[36:37] op_sel_hi:[1,0]
	v_pk_mul_f32 v[6:7], v[6:7], v[36:37] op_sel_hi:[1,0]
	v_pk_mul_f32 v[8:9], v[8:9], v[36:37] op_sel_hi:[1,0]
	s_waitcnt vmcnt(11)
	v_lshlrev_b32_e32 v46, 16, v42
	v_and_b32_e32 v47, 0xffff0000, v42
	v_lshlrev_b32_e32 v42, 16, v43
	v_and_b32_e32 v43, 0xffff0000, v43
	s_waitcnt vmcnt(10)
	v_lshlrev_b32_e32 v48, 16, v44
	v_and_b32_e32 v49, 0xffff0000, v44
	v_lshlrev_b32_e32 v44, 16, v45
	v_and_b32_e32 v45, 0xffff0000, v45
	v_pk_fma_f32 v[2:3], v[2:3], v[46:47], v[48:49]
	v_pk_fma_f32 v[4:5], v[4:5], v[42:43], v[44:45]
	v_cvt_pk_bf16_f32 v2, v2, v3
	v_cvt_pk_bf16_f32 v3, v4, v5
	global_store_dwordx2 v[40:41], v[2:3], off offset:2560
	s_waitcnt vmcnt(10)
	s_nop 0
	v_mov_b32_e32 v2, v226
	v_mov_b32_e32 v3, v227
	s_nop 0
	s_waitcnt vmcnt(9)
	s_nop 0
	v_mov_b32_e32 v4, v228
	v_mov_b32_e32 v5, v229
	s_waitcnt vmcnt(11)
	v_lshlrev_b32_e32 v40, 16, v2
	v_and_b32_e32 v41, 0xffff0000, v2
	s_waitcnt vmcnt(11)
	v_lshlrev_b32_e32 v42, 16, v4
	v_and_b32_e32 v43, 0xffff0000, v4
	v_lshlrev_b32_e32 v2, 16, v3
	v_and_b32_e32 v3, 0xffff0000, v3
	v_lshlrev_b32_e32 v4, 16, v5
	v_and_b32_e32 v5, 0xffff0000, v5
	v_pk_fma_f32 v[6:7], v[6:7], v[40:41], v[42:43]
	v_pk_fma_f32 v[2:3], v[8:9], v[2:3], v[4:5]
	v_cvt_pk_bf16_f32 v4, v6, v7
	v_cvt_pk_bf16_f32 v5, v2, v3
	global_store_dwordx2 v[34:35], v[4:5], off offset:16
	s_waitcnt vmcnt(9)
	s_nop 0
	v_mov_b32_e32 v2, v230
	v_mov_b32_e32 v3, v231
	s_nop 0
	s_waitcnt vmcnt(8)
	s_nop 0
	v_mov_b32_e32 v4, v232
	v_mov_b32_e32 v5, v233
	v_pk_mul_f32 v[6:7], v[10:11], v[36:37] op_sel_hi:[1,0]
	s_waitcnt vmcnt(12)
	v_lshlrev_b32_e32 v8, 16, v2
	v_and_b32_e32 v9, 0xffff0000, v2
	s_waitcnt vmcnt(12)
	v_lshlrev_b32_e32 v10, 16, v4
	v_and_b32_e32 v11, 0xffff0000, v4
	v_pk_fma_f32 v[6:7], v[6:7], v[8:9], v[10:11]
	v_pk_mul_f32 v[8:9], v[12:13], v[36:37] op_sel_hi:[1,0]
	v_lshlrev_b32_e32 v2, 16, v3
	v_and_b32_e32 v3, 0xffff0000, v3
	v_lshlrev_b32_e32 v4, 16, v5
	v_and_b32_e32 v5, 0xffff0000, v5
	v_pk_fma_f32 v[2:3], v[8:9], v[2:3], v[4:5]
	v_cvt_pk_bf16_f32 v4, v6, v7
	v_cvt_pk_bf16_f32 v5, v2, v3
	global_store_dwordx2 v[34:35], v[4:5], off offset:32
	global_load_dwordx2 v[226:227], v[38:39], off offset:96
	global_load_dwordx2 v[228:229], v[34:35], off offset:96
	global_load_dwordx2 v[230:231], v[38:39], off offset:112
	global_load_dwordx2 v[232:233], v[34:35], off offset:112
	s_waitcnt vmcnt(12)
; #define LAS __attribute__((address_space(3)))
; __device__ __forceinline__ unsigned pk2(float lo, float hi) { f32x2_t v = {lo, hi}; bf16x2_t b = __builtin_convertvector(v, bf16x2_t); return __builtin_bit_cast(unsigned, b); }
; __device__ __forceinline__ float bflo(unsigned u) { return __uint_as_float(u << 16); }
; __device__ __forceinline__ float bfhi(unsigned u) { return __uint_as_float(u & 0xffff0000u); }
; __device__ __forceinline__ int fresh_tid(int wave_s) { return wave_s * 64 + lane_id(); }
; template <int DV, bool ACCUM>
; __device__ __forceinline__ void attn_store(const f32x16 (&o)[DV / 32], const bf16_t* gate_row, bf16_t* merged_row, int h) {
; #pragma unroll
;     for (int db = 0; db < DV / 32; ++db)
; #pragma unroll
;         for (int rg = 0; rg < 4; ++rg) {
;             const int d = 32 * db + 8 * rg + 4 * h;
;             const u32x2 g = *(const u32x2*)(gate_row + d);
;             float v0 = o[db][4 * rg + 0] * bflo(g.x), v1 = o[db][4 * rg + 1] * bfhi(g.x), v2 = o[db][4 * rg + 2] * bflo(g.y), v3 = o[db][4 * rg + 3] * bfhi(g.y);
;             if (ACCUM) { const u32x2 mm = *(const u32x2*)(merged_row + d); v0 += bflo(mm.x); v1 += bfhi(mm.x); v2 += bflo(mm.y); v3 += bfhi(mm.y); }
;             u32x2 w; w.x = pk2(v0, v1); w.y = pk2(v2, v3);
;             *(u32x2*)(merged_row + d) = w;
;             if (rg == 3) __builtin_amdgcn_sched_barrier(0);
;         }
; __global__ void __launch_bounds__(512) fwd_megakernel(Args a) {
;     ...
;                 for (int g = 0; g < 4; ++g) {
;                     const int hh = 4 * kvh + g;
;                     __syncthreads();
;                     build_lut_pad((LAS float*)(lds + SW_LUT), rel_table, hh, wave_s);
;                     __syncthreads();
;                     const float sink2 = a.in[12][L * 16 + hh] * LOG2E;
;                     f32x16 o[2];
;                     flash_core<64, 64, 1, true>(lds, wave_s, ACT + (tok0 + q0) * INP + C_QB + 64 * hh, INP, nullptr, 0, nullptr, 0, nullptr, 0, q0, wlo, whi,
;                                                 (const LAS float*)(lds + SW_LUT), sink2, o, klo);
;                     const int l2 = fresh_tid(wave_s) & 63;
;                     bf16_t* row = ACT + (tok0 + q0 + 32 * wave + (l2 & 31)) * INP;
;                     attn_store<64, true>(o, row + C_GB + 64 * hh, row + C_GA + 64 * hh, l2 >> 5);
;                 }
	s_nop 0
	v_mov_b32_e32 v4, v234
	v_mov_b32_e32 v5, v235
	s_nop 0
	s_waitcnt vmcnt(11)
	s_nop 0
	v_mov_b32_e32 v2, v236
	v_mov_b32_e32 v3, v237
	v_pk_mul_f32 v[6:7], v[14:15], v[36:37] op_sel_hi:[1,0]
	s_waitcnt vmcnt(17)
	v_lshlrev_b32_e32 v8, 16, v4
	v_and_b32_e32 v9, 0xffff0000, v4
	s_waitcnt vmcnt(17)
	v_lshlrev_b32_e32 v10, 16, v2
	v_and_b32_e32 v11, 0xffff0000, v2
	v_pk_fma_f32 v[6:7], v[6:7], v[8:9], v[10:11]
	v_pk_mul_f32 v[8:9], v[16:17], v[36:37] op_sel_hi:[1,0]
	v_lshlrev_b32_e32 v4, 16, v5
	v_and_b32_e32 v5, 0xffff0000, v5
	v_lshlrev_b32_e32 v2, 16, v3
	v_and_b32_e32 v3, 0xffff0000, v3
	v_pk_fma_f32 v[2:3], v[8:9], v[4:5], v[2:3]
	v_cvt_pk_bf16_f32 v4, v6, v7
	v_cvt_pk_bf16_f32 v5, v2, v3
	global_store_dwordx2 v[34:35], v[4:5], off offset:48
	s_waitcnt vmcnt(11)
	s_nop 0
	v_mov_b32_e32 v2, v242
	v_mov_b32_e32 v3, v243
	s_nop 0
	s_waitcnt vmcnt(10)
	s_nop 0
	v_mov_b32_e32 v4, v244
	v_mov_b32_e32 v5, v245
	v_pk_mul_f32 v[6:7], v[18:19], v[36:37] op_sel_hi:[1,0]
	s_waitcnt vmcnt(18)
	v_lshlrev_b32_e32 v8, 16, v2
	v_and_b32_e32 v9, 0xffff0000, v2
	s_waitcnt vmcnt(18)
	v_lshlrev_b32_e32 v10, 16, v4
	v_and_b32_e32 v11, 0xffff0000, v4
	v_pk_fma_f32 v[6:7], v[6:7], v[8:9], v[10:11]
	v_pk_mul_f32 v[8:9], v[20:21], v[36:37] op_sel_hi:[1,0]
	v_lshlrev_b32_e32 v2, 16, v3
	v_and_b32_e32 v3, 0xffff0000, v3
	v_lshlrev_b32_e32 v4, 16, v5
	v_and_b32_e32 v5, 0xffff0000, v5
	v_pk_fma_f32 v[2:3], v[8:9], v[2:3], v[4:5]
	v_cvt_pk_bf16_f32 v4, v6, v7
	v_cvt_pk_bf16_f32 v5, v2, v3
	global_store_dwordx2 v[34:35], v[4:5], off offset:64
	s_waitcnt vmcnt(10)
	s_nop 0
	v_mov_b32_e32 v2, v246
	v_mov_b32_e32 v3, v247
	s_nop 0
	s_waitcnt vmcnt(9)
	s_nop 0
	v_mov_b32_e32 v4, v248
	v_mov_b32_e32 v5, v249
	v_pk_mul_f32 v[6:7], v[22:23], v[36:37] op_sel_hi:[1,0]
	s_waitcnt vmcnt(19)
	v_lshlrev_b32_e32 v8, 16, v2
	v_and_b32_e32 v9, 0xffff0000, v2
	s_waitcnt vmcnt(19)
	v_lshlrev_b32_e32 v10, 16, v4
	v_and_b32_e32 v11, 0xffff0000, v4
	v_pk_fma_f32 v[6:7], v[6:7], v[8:9], v[10:11]
	v_pk_mul_f32 v[8:9], v[24:25], v[36:37] op_sel_hi:[1,0]
	v_lshlrev_b32_e32 v2, 16, v3
	v_and_b32_e32 v3, 0xffff0000, v3
	v_lshlrev_b32_e32 v4, 16, v5
	v_and_b32_e32 v5, 0xffff0000, v5
	v_pk_fma_f32 v[2:3], v[8:9], v[2:3], v[4:5]
	v_cvt_pk_bf16_f32 v4, v6, v7
	v_cvt_pk_bf16_f32 v5, v2, v3
	global_store_dwordx2 v[34:35], v[4:5], off offset:80
	s_waitcnt vmcnt(6)
	s_nop 0
	v_mov_b32_e32 v2, v226
	v_mov_b32_e32 v3, v227
	s_nop 0
	s_waitcnt vmcnt(5)
	s_nop 0
	v_mov_b32_e32 v4, v228
	v_mov_b32_e32 v5, v229
	v_pk_mul_f32 v[6:7], v[26:27], v[36:37] op_sel_hi:[1,0]
	s_waitcnt vmcnt(20)
	v_lshlrev_b32_e32 v8, 16, v2
	v_and_b32_e32 v9, 0xffff0000, v2
	s_waitcnt vmcnt(20)
	v_lshlrev_b32_e32 v10, 16, v4
	v_and_b32_e32 v11, 0xffff0000, v4
	v_pk_fma_f32 v[6:7], v[6:7], v[8:9], v[10:11]
	v_pk_mul_f32 v[8:9], v[28:29], v[36:37] op_sel_hi:[1,0]
	v_lshlrev_b32_e32 v2, 16, v3
	v_and_b32_e32 v3, 0xffff0000, v3
	v_lshlrev_b32_e32 v4, 16, v5
	v_and_b32_e32 v5, 0xffff0000, v5
	v_pk_fma_f32 v[2:3], v[8:9], v[2:3], v[4:5]
	v_cvt_pk_bf16_f32 v4, v6, v7
	v_cvt_pk_bf16_f32 v5, v2, v3
	global_store_dwordx2 v[34:35], v[4:5], off offset:96
	s_waitcnt vmcnt(5)
	s_nop 0
	v_mov_b32_e32 v2, v230
	v_mov_b32_e32 v3, v231
	s_nop 0
	s_waitcnt vmcnt(4)
	s_nop 0
	v_mov_b32_e32 v4, v232
	v_mov_b32_e32 v5, v233
	v_pk_mul_f32 v[6:7], v[30:31], v[36:37] op_sel_hi:[1,0]
	s_waitcnt vmcnt(21)
	v_lshlrev_b32_e32 v8, 16, v2
	v_and_b32_e32 v9, 0xffff0000, v2
	s_waitcnt vmcnt(21)
	v_lshlrev_b32_e32 v10, 16, v4
	v_and_b32_e32 v11, 0xffff0000, v4
	v_pk_fma_f32 v[6:7], v[6:7], v[8:9], v[10:11]
	v_pk_mul_f32 v[8:9], v[32:33], v[36:37] op_sel_hi:[1,0]
	v_lshlrev_b32_e32 v2, 16, v3
	v_and_b32_e32 v3, 0xffff0000, v3
	v_lshlrev_b32_e32 v4, 16, v5
	v_and_b32_e32 v5, 0xffff0000, v5
	v_pk_fma_f32 v[2:3], v[8:9], v[2:3], v[4:5]
	v_cvt_pk_bf16_f32 v4, v6, v7
	v_cvt_pk_bf16_f32 v5, v2, v3
	global_store_dwordx2 v[34:35], v[4:5], off offset:112
	s_add_i32 s34, s34, 1
	s_cmp_eq_u32 s34, 4
	s_cbranch_scc1 .LBB0_808
